# MF=4 DMA GEMM loops: second K-step DMA issues moved into the first six MFMA gaps after the barrier (on top of the front-interleaved MF=2 loops)
# baseline (speedup 1.0000x reference)
; #define MFMA32(a, b, c) __builtin_amdgcn_mfma_f32_32x32x16_bf16((a), (b), (c), 0, 0, 0)
; template <int MF, int BK, class Epi>
; DI void gemm_phase_t(char* lds, const GemmDesc g, const Epi epi) {
;     ...
;     for (int kt = 0; kt < nk; ++kt) {
;       __syncthreads();
;       const u16* sA = sbase + (kt & 1) * STG;
;       const u16* sB = sA + BM * LS;
;       if (kt + 1 < nk) {
;         u16* nA = sbase + ((kt + 1) & 1) * STG;
; #pragma unroll
;         for (int j = 0; j < APT; ++j) *(u32x4*)(nA + (lr + RSTEP * j) * LS + lc * 8) = ra[j];
; #pragma unroll
;         for (int j = 0; j < BPT; ++j) *(u32x4*)(nA + BM * LS + (lr + RSTEP * j) * LS + lc * 8) = rb[j];
;         if (kt + 2 < nk) {
; #pragma unroll
;           for (int j = 0; j < APT; ++j) ra[j] = *(const u32x4*)(Ap + (size_t)j * RSTEP * g.lda + (kt + 2) * BK);
; #pragma unroll
;           for (int j = 0; j < BPT; ++j) rb[j] = *(const u32x4*)(Bp + (size_t)j * RSTEP * g.ldb + (kt + 2) * BK);
;         }
;       }
;       bf16x8 af[NKK][MF], bfr[NKK][2];
; #pragma unroll
;       for (int kk = 0; kk < NKK; ++kk) {
; #pragma unroll
;         for (int ni = 0; ni < 2; ++ni) bfr[kk][ni] = *(const bf16x8*)(sB + (wn * 64 + ni * 32 + l31) * LS + kk * 16 + h * 8);
; #pragma unroll
;         for (int mi = 0; mi < MF; ++mi) af[kk][mi] = *(const bf16x8*)(sA + (wm * (MF * 32) + mi * 32 + l31) * LS + kk * 16 + h * 8);
;       }
;       __builtin_amdgcn_sched_barrier(0);
; #pragma unroll
;       for (int kk = 0; kk < NKK; ++kk)
; #pragma unroll
;         for (int mi = 0; mi < MF; ++mi)
; #pragma unroll
;           for (int ni = 0; ni < 2; ++ni) acc[mi][ni] = MFMA32(bfr[kk][ni], af[kk][mi], acc[mi][ni]);
.LBB0_288:
	v_lshl_add_u64 v[186:187], v[164:165], 0, s[4:5]
	v_add_co_u32_e32 v194, vcc, s11, v186
	v_lshl_add_u64 v[204:205], v[168:169], 0, s[4:5]
	s_nop 0
	v_addc_co_u32_e32 v195, vcc, 0, v187, vcc
	v_add_co_u32_e32 v198, vcc, s12, v186
	s_mov_b32 s10, 0x164c000
	s_nop 0
	v_addc_co_u32_e32 v199, vcc, 0, v187, vcc
	v_add_co_u32_e32 v200, vcc, s13, v186
	s_waitcnt lgkmcnt(0)
	s_nop 0
	v_addc_co_u32_e32 v201, vcc, 0, v187, vcc
	v_add_co_u32_e32 v246, vcc, s14, v186
	s_waitcnt vmcnt(6)
	s_barrier
	s_nop 0
	v_addc_co_u32_e32 v247, vcc, 0, v187, vcc
	v_add_co_u32_e32 v248, vcc, s10, v204
	s_mov_b32 s10, 0x166c000
	s_nop 0
	v_addc_co_u32_e32 v249, vcc, 0, v205, vcc
	v_add_co_u32_e32 v216, vcc, s10, v204
	s_add_i32 m0, s100, 0xffffff80
	s_nop 0
	global_load_lds_dwordx4 v[194:195], off offset:128
	s_add_i32 m0, s100, 0xf80
	s_nop 0
	global_load_lds_dwordx4 v[198:199], off offset:128
	s_add_i32 m0, s100, 0x1f80
	s_nop 0
	global_load_lds_dwordx4 v[200:201], off offset:128
	s_add_i32 m0, s100, 0x2f80
	s_nop 0
	global_load_lds_dwordx4 v[246:247], off offset:128
	v_addc_co_u32_e32 v217, vcc, 0, v205, vcc
	s_add_i32 m0, s100, 0x3f80
	s_nop 0
	global_load_lds_dwordx4 v[248:249], off offset:128
	s_add_i32 m0, s100, 0x4f80
	s_nop 0
	global_load_lds_dwordx4 v[216:217], off offset:128
	v_add_u32_e32 v178, s98, v175
	v_add_u32_e32 v179, s98, v176
	v_add_u32_e32 v180, s98, v174
	v_add_u32_e32 v181, s98, v173
	ds_read_b128 v[132:135], v180
	ds_read_b128 v[222:225], v181
	ds_read_b128 v[136:139], v180 offset:2048
	ds_read_b128 v[226:229], v181 offset:2048
	ds_read_b128 v[140:143], v178
	ds_read_b128 v[144:147], v179
	ds_read_b128 v[148:151], v178 offset:2048
	ds_read_b128 v[152:155], v179 offset:2048
	ds_read_b128 v[230:233], v178 offset:4096
	ds_read_b128 v[234:237], v179 offset:4096
	ds_read_b128 v[238:241], v178 offset:6144
	ds_read_b128 v[242:245], v179 offset:6144
	s_waitcnt lgkmcnt(7)
	v_mfma_f32_32x32x16_bf16 v[116:131], v[132:135], v[140:143], v[116:131]
	s_waitcnt lgkmcnt(0)
	s_waitcnt vmcnt(6)
	s_barrier
	v_mfma_f32_32x32x16_bf16 v[100:115], v[136:139], v[140:143], v[100:115]
	s_add_i32 m0, s98, 0xffffff40
	s_nop 0
	global_load_lds_dwordx4 v[194:195], off offset:192
	v_mfma_f32_32x32x16_bf16 v[84:99], v[132:135], v[148:151], v[84:99]
	s_add_i32 m0, s98, 0xf40
	s_nop 0
	global_load_lds_dwordx4 v[198:199], off offset:192
	v_mfma_f32_32x32x16_bf16 v[68:83], v[136:139], v[148:151], v[68:83]
	s_add_i32 m0, s98, 0x1f40
	s_nop 0
	global_load_lds_dwordx4 v[200:201], off offset:192
	v_mfma_f32_32x32x16_bf16 v[52:67], v[132:135], v[230:233], v[52:67]
	s_add_i32 m0, s98, 0x2f40
	s_nop 0
	global_load_lds_dwordx4 v[246:247], off offset:192
	v_mfma_f32_32x32x16_bf16 v[36:51], v[136:139], v[230:233], v[36:51]
	s_add_i32 m0, s98, 0x3f40
	s_nop 0
	global_load_lds_dwordx4 v[248:249], off offset:192
	v_mfma_f32_32x32x16_bf16 v[20:35], v[132:135], v[238:241], v[20:35]
	s_add_i32 m0, s98, 0x4f40
	s_nop 0
	global_load_lds_dwordx4 v[216:217], off offset:192
	v_mfma_f32_32x32x16_bf16 v[4:19], v[136:139], v[238:241], v[4:19]
	v_mfma_f32_32x32x16_bf16 v[116:131], v[222:225], v[144:147], v[116:131]
	v_mfma_f32_32x32x16_bf16 v[100:115], v[226:229], v[144:147], v[100:115]
	v_mfma_f32_32x32x16_bf16 v[84:99], v[222:225], v[152:155], v[84:99]
	v_mfma_f32_32x32x16_bf16 v[68:83], v[226:229], v[152:155], v[68:83]
	v_add_u32_e32 v132, s99, v175
	v_add_u32_e32 v133, s99, v176
	v_add_u32_e32 v134, s99, v174
	v_add_u32_e32 v135, s99, v173
	ds_read_b128 v[178:181], v134
	ds_read_b128 v[182:185], v135
	ds_read_b128 v[186:189], v134 offset:2048
	ds_read_b128 v[190:193], v135 offset:2048
	v_mfma_f32_32x32x16_bf16 v[52:67], v[222:225], v[234:237], v[52:67]
	v_mfma_f32_32x32x16_bf16 v[36:51], v[226:229], v[234:237], v[36:51]
	v_mfma_f32_32x32x16_bf16 v[20:35], v[222:225], v[242:245], v[20:35]
	ds_read_b128 v[204:207], v132
	ds_read_b128 v[218:221], v133
	ds_read_b128 v[222:225], v132 offset:2048
	ds_read_b128 v[230:233], v133 offset:2048
	ds_read_b128 v[234:237], v132 offset:4096
	ds_read_b128 v[238:241], v133 offset:4096
	ds_read_b128 v[246:249], v132 offset:6144
	ds_read_b128 v[198:201], v133 offset:6144
	v_mfma_f32_32x32x16_bf16 v[4:19], v[226:229], v[242:245], v[4:19]
	s_waitcnt lgkmcnt(7)
	v_mfma_f32_32x32x16_bf16 v[116:131], v[178:181], v[204:207], v[116:131]
	s_add_u32 s4, s4, 0x80
	s_addc_u32 s5, s5, 0
	s_cmpk_eq_i32 s4, 0x780
	v_mfma_f32_32x32x16_bf16 v[100:115], v[186:189], v[204:207], v[100:115]
	s_waitcnt lgkmcnt(5)
	v_mfma_f32_32x32x16_bf16 v[84:99], v[178:181], v[222:225], v[84:99]
	v_mfma_f32_32x32x16_bf16 v[68:83], v[186:189], v[222:225], v[68:83]
	s_waitcnt lgkmcnt(3)
	v_mfma_f32_32x32x16_bf16 v[52:67], v[178:181], v[234:237], v[52:67]
	v_mfma_f32_32x32x16_bf16 v[36:51], v[186:189], v[234:237], v[36:51]
	s_waitcnt lgkmcnt(1)
	v_mfma_f32_32x32x16_bf16 v[20:35], v[178:181], v[246:249], v[20:35]
	v_mfma_f32_32x32x16_bf16 v[4:19], v[186:189], v[246:249], v[4:19]
	v_mfma_f32_32x32x16_bf16 v[116:131], v[182:185], v[218:221], v[116:131]
	v_mfma_f32_32x32x16_bf16 v[100:115], v[190:193], v[218:221], v[100:115]
	v_mfma_f32_32x32x16_bf16 v[84:99], v[182:185], v[230:233], v[84:99]
	v_mfma_f32_32x32x16_bf16 v[68:83], v[190:193], v[230:233], v[68:83]
	v_mfma_f32_32x32x16_bf16 v[52:67], v[182:185], v[238:241], v[52:67]
	v_mfma_f32_32x32x16_bf16 v[36:51], v[190:193], v[238:241], v[36:51]
	s_waitcnt lgkmcnt(0)
	v_mfma_f32_32x32x16_bf16 v[20:35], v[182:185], v[198:201], v[20:35]
	v_mfma_f32_32x32x16_bf16 v[4:19], v[190:193], v[198:201], v[4:19]
	s_mov_b32 s101, s100
	s_mov_b32 s100, s99
	s_mov_b32 s99, s98
	s_mov_b32 s98, s101
	s_cbranch_scc0 .LBB0_288
	s_waitcnt vmcnt(6)
	s_barrier
; #define MFMA32(a, b, c) __builtin_amdgcn_mfma_f32_32x32x16_bf16((a), (b), (c), 0, 0, 0)
; DI unsigned pack2(float a, float b) { f2_t v = {a, b}; return __builtin_bit_cast(unsigned, __builtin_convertvector(v, bf2_t)); }
; DI float siluf(float x) { return x * __builtin_amdgcn_rcpf(1.f + __expf(-x)); }
; template <int MF, int BK, class Epi>
; DI void gemm_phase_t(char* lds, const GemmDesc g, const Epi epi) {
;     ...
;       for (int kk = 0; kk < NKK; ++kk) {
; #pragma unroll
;         for (int ni = 0; ni < 2; ++ni) bfr[kk][ni] = *(const bf16x8*)(sB + (wn * 64 + ni * 32 + l31) * LS + kk * 16 + h * 8);
; #pragma unroll
;         for (int mi = 0; mi < MF; ++mi) af[kk][mi] = *(const bf16x8*)(sA + (wm * (MF * 32) + mi * 32 + l31) * LS + kk * 16 + h * 8);
;       }
;       __builtin_amdgcn_sched_barrier(0);
; #pragma unroll
;       for (int kk = 0; kk < NKK; ++kk)
; #pragma unroll
;         for (int mi = 0; mi < MF; ++mi)
; #pragma unroll
;           for (int ni = 0; ni < 2; ++ni) acc[mi][ni] = MFMA32(bfr[kk][ni], af[kk][mi], acc[mi][ni]);
;   template <int MF> DI void operator()(f32x16 (&acc)[MF][2], int mb, int nb, int l31, int h) const {
;     ...
;     for (int mi = 0; mi < MF; ++mi) {
;       const int row = mb + mi * 32 + l31;
; #pragma unroll
;       for (int gp = 0; gp < 2; ++gp) {
;         const int j0 = (nb >> 1) + 16 * h + 8 * gp;
;         float v[8];
; #pragma unroll
;         for (int i = 0; i < 8; ++i) v[i] = siluf(acc[mi][0][8 * gp + i]) * acc[mi][1][8 * gp + i];
;         *(u32x4*)(act + (size_t)row * FF + j0) = (u32x4){pack2(v[0], v[1]), pack2(v[2], v[3]), pack2(v[4], v[5]), pack2(v[6], v[7])};
	v_add_u32_e32 v222, s98, v175
	v_add_u32_e32 v223, s98, v176
	v_add_u32_e32 v224, s98, v174
	v_add_u32_e32 v225, s98, v173
	ds_read_b128 v[132:135], v224
	ds_read_b128 v[136:139], v225
	ds_read_b128 v[140:143], v224 offset:2048
	ds_read_b128 v[144:147], v225 offset:2048
	ds_read_b128 v[148:151], v222
	ds_read_b128 v[152:155], v223
	ds_read_b128 v[178:181], v222 offset:2048
	ds_read_b128 v[182:185], v223 offset:2048
	ds_read_b128 v[186:189], v222 offset:4096
	ds_read_b128 v[190:193], v223 offset:4096
	ds_read_b128 v[204:207], v222 offset:6144
	ds_read_b128 v[218:221], v223 offset:6144
	s_waitcnt lgkmcnt(7)
	v_mfma_f32_32x32x16_bf16 v[116:131], v[132:135], v[148:151], v[116:131]
	s_waitcnt lgkmcnt(0)
	s_waitcnt vmcnt(0)
	s_barrier
	v_mfma_f32_32x32x16_bf16 v[100:115], v[140:143], v[148:151], v[100:115]
	v_mfma_f32_32x32x16_bf16 v[84:99], v[132:135], v[178:181], v[84:99]
	v_mfma_f32_32x32x16_bf16 v[68:83], v[140:143], v[178:181], v[68:83]
	v_mfma_f32_32x32x16_bf16 v[52:67], v[132:135], v[186:189], v[52:67]
	v_mfma_f32_32x32x16_bf16 v[36:51], v[140:143], v[186:189], v[36:51]
	v_mfma_f32_32x32x16_bf16 v[20:35], v[132:135], v[204:207], v[20:35]
	v_mfma_f32_32x32x16_bf16 v[4:19], v[140:143], v[204:207], v[4:19]
	v_mfma_f32_32x32x16_bf16 v[116:131], v[136:139], v[152:155], v[116:131]
	v_mfma_f32_32x32x16_bf16 v[100:115], v[144:147], v[152:155], v[100:115]
	v_mfma_f32_32x32x16_bf16 v[84:99], v[136:139], v[182:185], v[84:99]
	v_mfma_f32_32x32x16_bf16 v[68:83], v[144:147], v[182:185], v[68:83]
	v_mfma_f32_32x32x16_bf16 v[52:67], v[136:139], v[190:193], v[52:67]
	v_mfma_f32_32x32x16_bf16 v[36:51], v[144:147], v[190:193], v[36:51]
	v_mfma_f32_32x32x16_bf16 v[20:35], v[136:139], v[218:221], v[20:35]
	v_mfma_f32_32x32x16_bf16 v[4:19], v[144:147], v[218:221], v[4:19]
	v_add_u32_e32 v226, s99, v175
	v_add_u32_e32 v227, s99, v176
	v_add_u32_e32 v228, s99, v174
	v_add_u32_e32 v229, s99, v173
	s_mov_b32 s101, s100
	s_mov_b32 s100, s99
	s_mov_b32 s99, s98
	s_mov_b32 s98, s101
	ds_read_b128 v[132:135], v226 offset:6144
	ds_read_b128 v[136:139], v227 offset:6144
	ds_read_b128 v[140:143], v227 offset:4096
	ds_read_b128 v[144:147], v227 offset:2048
	ds_read_b128 v[148:151], v226
	ds_read_b128 v[152:155], v227
	ds_read_b128 v[178:181], v229 offset:2048
	ds_read_b128 v[182:185], v228
	ds_read_b128 v[186:189], v229
	ds_read_b128 v[190:193], v226 offset:4096
	ds_read_b128 v[204:207], v226 offset:2048
	ds_read_b128 v[218:221], v228 offset:2048
	s_waitcnt lgkmcnt(4)
	v_mfma_f32_32x32x16_bf16 v[116:131], v[182:185], v[148:151], v[116:131]
	s_waitcnt lgkmcnt(3)
	v_mfma_f32_32x32x16_bf16 v[116:131], v[186:189], v[152:155], v[116:131]
	s_waitcnt lgkmcnt(2)
	v_mfma_f32_32x32x16_bf16 v[52:67], v[182:185], v[190:193], v[52:67]
	s_waitcnt lgkmcnt(0)
	v_mfma_f32_32x32x16_bf16 v[36:51], v[218:221], v[190:193], v[36:51]
	v_mfma_f32_32x32x16_bf16 v[20:35], v[182:185], v[132:135], v[20:35]
	v_mfma_f32_32x32x16_bf16 v[4:19], v[218:221], v[132:135], v[4:19]
	s_nop 5
	v_mul_f32_e32 v135, 0xbfb8aa3b, v116
	v_exp_f32_e32 v135, v135
	v_or_b32_e32 v132, s9, v170
	v_ashrrev_i32_e32 v132, 1, v132
	v_add_u32_e32 v134, s8, v172
	v_add_f32_e32 v135, 1.0, v135
	s_movk_i32 s8, 0x1600
	v_mfma_f32_32x32x16_bf16 v[100:115], v[218:221], v[148:151], v[100:115]
	v_mfma_f32_32x32x16_bf16 v[52:67], v[186:189], v[140:143], v[52:67]
	v_mfma_f32_32x32x16_bf16 v[36:51], v[178:181], v[140:143], v[36:51]
	v_rcp_f32_e32 v140, v135
	v_mul_f32_e32 v135, 0xbfb8aa3b, v117
	v_exp_f32_e32 v135, v135
	s_nop 0
	v_add_f32_e32 v135, 1.0, v135
	v_mfma_f32_32x32x16_bf16 v[100:115], v[178:181], v[152:155], v[100:115]
	v_rcp_f32_e32 v141, v135
	s_nop 0
	v_pk_mul_f32 v[116:117], v[116:117], v[140:141]
	v_mfma_f32_32x32x16_bf16 v[20:35], v[186:189], v[136:139], v[20:35]
	s_nop 7
	v_mul_f32_e64 v100, v100, v116
	v_mul_f32_e64 v101, v101, v117
	v_mul_f32_e32 v116, 0xbfb8aa3b, v118
	v_mul_f32_e32 v117, 0xbfb8aa3b, v119
	v_exp_f32_e32 v116, v116
	v_exp_f32_e32 v117, v117
	v_add_f32_e32 v116, 1.0, v116
	v_add_f32_e32 v117, 1.0, v117
	v_rcp_f32_e32 v116, v116
	v_rcp_f32_e32 v117, v117
	v_mfma_f32_32x32x16_bf16 v[4:19], v[178:181], v[136:139], v[4:19]
	v_or_b32_e32 v136, v132, v171
	v_mov_b64_e32 v[132:133], s[2:3]
	v_mul_f32_e64 v116, v118, v116
	v_mul_f32_e64 v117, v119, v117
	v_ashrrev_i32_e32 v137, 31, v136
	v_pk_mul_f32 v[116:117], v[102:103], v[116:117]
	v_mul_f32_e32 v102, 0xbfb8aa3b, v120
	v_mul_f32_e32 v103, 0xbfb8aa3b, v121
	v_exp_f32_e32 v102, v102
	v_exp_f32_e32 v103, v103
	v_mad_i64_i32 v[138:139], s[4:5], v134, s8, v[132:133]
	v_add_f32_e32 v102, 1.0, v102
	v_add_f32_e32 v103, 1.0, v103
	v_rcp_f32_e32 v102, v102
	v_rcp_f32_e32 v103, v103
	v_mfma_f32_32x32x16_bf16 v[84:99], v[182:185], v[204:207], v[84:99]
	v_mul_f32_e64 v102, v120, v102
	v_mul_f32_e64 v103, v121, v103
	v_mul_f32_e64 v104, v104, v102
	v_mul_f32_e64 v105, v105, v103
	v_mul_f32_e32 v102, 0xbfb8aa3b, v122
	v_mul_f32_e32 v103, 0xbfb8aa3b, v123
	v_exp_f32_e32 v102, v102
	v_exp_f32_e32 v103, v103
	v_cvt_pk_bf16_f32 v104, v104, v105
	v_mfma_f32_32x32x16_bf16 v[84:99], v[186:189], v[144:147], v[84:99]
	v_add_f32_e32 v102, 1.0, v102
	v_add_f32_e32 v103, 1.0, v103
	v_rcp_f32_e32 v102, v102
	v_rcp_f32_e32 v103, v103
	s_nop 0
	v_pk_mul_f32 v[102:103], v[122:123], v[102:103]
	s_nop 0
	v_pk_mul_f32 v[106:107], v[106:107], v[102:103]
	v_cvt_pk_bf16_f32 v102, v100, v101
	v_lshlrev_b64 v[100:101], 1, v[136:137]
	v_cvt_pk_bf16_f32 v103, v116, v117
	v_cvt_pk_bf16_f32 v105, v106, v107
	v_lshl_add_u64 v[106:107], v[138:139], 0, v[100:101]
	global_store_dwordx4 v[106:107], v[102:105], off
	v_mfma_f32_32x32x16_bf16 v[68:83], v[218:221], v[204:207], v[68:83]
	s_nop 0
; DI unsigned pack2(float a, float b) { f2_t v = {a, b}; return __builtin_bit_cast(unsigned, __builtin_convertvector(v, bf2_t)); }
; DI float siluf(float x) { return x * __builtin_amdgcn_rcpf(1.f + __expf(-x)); }
;   template <int MF> DI void operator()(f32x16 (&acc)[MF][2], int mb, int nb, int l31, int h) const {
;     ...
;     for (int mi = 0; mi < MF; ++mi) {
;       const int row = mb + mi * 32 + l31;
; #pragma unroll
;       for (int gp = 0; gp < 2; ++gp) {
;         const int j0 = (nb >> 1) + 16 * h + 8 * gp;
;         float v[8];
; #pragma unroll
;         for (int i = 0; i < 8; ++i) v[i] = siluf(acc[mi][0][8 * gp + i]) * acc[mi][1][8 * gp + i];
;         *(u32x4*)(act + (size_t)row * FF + j0) = (u32x4){pack2(v[0], v[1]), pack2(v[2], v[3]), pack2(v[4], v[5]), pack2(v[6], v[7])};
;       }
	v_mul_f32_e32 v102, 0xbfb8aa3b, v124
	v_mul_f32_e32 v103, 0xbfb8aa3b, v125
	v_mul_f32_e32 v104, 0xbfb8aa3b, v126
	v_mul_f32_e32 v105, 0xbfb8aa3b, v127
	v_exp_f32_e32 v102, v102
	v_exp_f32_e32 v103, v103
	v_exp_f32_e32 v104, v104
	v_exp_f32_e32 v105, v105
	v_add_f32_e32 v102, 1.0, v102
	v_add_f32_e32 v103, 1.0, v103
	v_add_f32_e32 v104, 1.0, v104
	v_add_f32_e32 v105, 1.0, v105
	v_rcp_f32_e32 v102, v102
	v_rcp_f32_e32 v103, v103
	v_rcp_f32_e32 v104, v104
	v_rcp_f32_e32 v105, v105
	v_mfma_f32_32x32x16_bf16 v[68:83], v[178:181], v[144:147], v[68:83]
	v_mul_f32_e64 v102, v124, v102
	v_mul_f32_e64 v103, v125, v103
	v_mul_f32_e64 v104, v126, v104
	v_mul_f32_e64 v105, v127, v105
	v_mul_f32_e64 v102, v108, v102
	v_mul_f32_e64 v103, v109, v103
	v_pk_mul_f32 v[104:105], v[110:111], v[104:105]
	v_mul_f32_e32 v108, 0xbfb8aa3b, v128
	v_mul_f32_e32 v109, 0xbfb8aa3b, v129
	v_mul_f32_e32 v110, 0xbfb8aa3b, v130
	v_mul_f32_e32 v111, 0xbfb8aa3b, v131
	v_exp_f32_e32 v108, v108
	v_exp_f32_e32 v109, v109
	v_exp_f32_e32 v110, v110
	v_exp_f32_e32 v111, v111
	v_add_f32_e32 v108, 1.0, v108
	v_add_f32_e32 v109, 1.0, v109
	v_add_f32_e32 v110, 1.0, v110
	v_add_f32_e32 v111, 1.0, v111
	v_rcp_f32_e32 v108, v108
	v_rcp_f32_e32 v109, v109
	v_rcp_f32_e32 v110, v110
	v_rcp_f32_e32 v111, v111
	v_cvt_pk_bf16_f32 v102, v102, v103
	v_pk_mul_f32 v[108:109], v[128:129], v[108:109]
	v_cvt_pk_bf16_f32 v103, v104, v105
	v_pk_mul_f32 v[110:111], v[130:131], v[110:111]
	v_pk_mul_f32 v[108:109], v[112:113], v[108:109]
	v_pk_mul_f32 v[110:111], v[114:115], v[110:111]
	v_cvt_pk_bf16_f32 v104, v108, v109
	v_cvt_pk_bf16_f32 v105, v110, v111
	global_store_dwordx4 v[106:107], v[102:105], off offset:16
	s_nop 1
	v_mul_f32_e32 v104, 0xbfb8aa3b, v84
	v_mul_f32_e32 v105, 0xbfb8aa3b, v85
	v_exp_f32_e32 v104, v104
	v_exp_f32_e32 v105, v105
	v_or_b32_e32 v102, 32, v134
	v_mad_i64_i32 v[102:103], s[4:5], v102, s8, v[132:133]
	v_add_f32_e32 v104, 1.0, v104
	v_add_f32_e32 v105, 1.0, v105
	v_rcp_f32_e32 v104, v104
	v_rcp_f32_e32 v105, v105
	s_nop 0
	v_pk_mul_f32 v[84:85], v[84:85], v[104:105]
	s_nop 0
	v_pk_mul_f32 v[68:69], v[68:69], v[84:85]
	v_mul_f32_e32 v84, 0xbfb8aa3b, v86
	v_mul_f32_e32 v85, 0xbfb8aa3b, v87
	v_exp_f32_e32 v84, v84
	v_exp_f32_e32 v85, v85
	v_cvt_pk_bf16_f32 v68, v68, v69
	v_add_f32_e32 v84, 1.0, v84
	v_add_f32_e32 v85, 1.0, v85
	v_rcp_f32_e32 v84, v84
	v_rcp_f32_e32 v85, v85
	s_nop 0
	v_pk_mul_f32 v[84:85], v[86:87], v[84:85]
	s_nop 0
	v_pk_mul_f32 v[70:71], v[70:71], v[84:85]
	v_mul_f32_e32 v84, 0xbfb8aa3b, v88
	v_mul_f32_e32 v85, 0xbfb8aa3b, v89
	v_exp_f32_e32 v84, v84
	v_exp_f32_e32 v85, v85
	v_cvt_pk_bf16_f32 v69, v70, v71
	v_add_f32_e32 v84, 1.0, v84
	v_add_f32_e32 v85, 1.0, v85
	v_rcp_f32_e32 v84, v84
	v_rcp_f32_e32 v85, v85
	s_nop 0
	v_pk_mul_f32 v[84:85], v[88:89], v[84:85]
	s_nop 0
	v_pk_mul_f32 v[72:73], v[72:73], v[84:85]
	v_mul_f32_e32 v84, 0xbfb8aa3b, v90
	v_mul_f32_e32 v85, 0xbfb8aa3b, v91
	v_exp_f32_e32 v84, v84
	v_exp_f32_e32 v85, v85
	v_cvt_pk_bf16_f32 v70, v72, v73
	v_lshl_add_u64 v[72:73], v[102:103], 0, v[100:101]
	v_add_f32_e32 v84, 1.0, v84
	v_add_f32_e32 v85, 1.0, v85
	v_rcp_f32_e32 v84, v84
	v_rcp_f32_e32 v85, v85
	s_nop 0
	v_pk_mul_f32 v[84:85], v[90:91], v[84:85]
	s_nop 0
	v_pk_mul_f32 v[74:75], v[74:75], v[84:85]
	s_nop 0
	v_cvt_pk_bf16_f32 v71, v74, v75
	global_store_dwordx4 v[72:73], v[68:71], off
	v_mul_f32_e32 v74, 0xbfb8aa3b, v96
	v_mul_f32_e32 v75, 0xbfb8aa3b, v97
	v_mul_f32_e32 v68, 0xbfb8aa3b, v92
	v_mul_f32_e32 v69, 0xbfb8aa3b, v93
	v_exp_f32_e32 v68, v68
	v_exp_f32_e32 v69, v69
	v_mul_f32_e32 v70, 0xbfb8aa3b, v94
	v_mul_f32_e32 v71, 0xbfb8aa3b, v95
	v_add_f32_e32 v68, 1.0, v68
	v_add_f32_e32 v69, 1.0, v69
	v_rcp_f32_e32 v68, v68
	v_rcp_f32_e32 v69, v69
	v_exp_f32_e32 v70, v70
	v_exp_f32_e32 v71, v71
	v_exp_f32_e32 v74, v74
	v_pk_mul_f32 v[68:69], v[92:93], v[68:69]
	v_exp_f32_e32 v75, v75
	v_pk_mul_f32 v[68:69], v[76:77], v[68:69]
	v_mul_f32_e32 v76, 0xbfb8aa3b, v98
	v_mul_f32_e32 v77, 0xbfb8aa3b, v99
	v_exp_f32_e32 v76, v76
	v_exp_f32_e32 v77, v77
	v_add_f32_e32 v70, 1.0, v70
	v_add_f32_e32 v71, 1.0, v71
	v_add_f32_e32 v74, 1.0, v74
	v_add_f32_e32 v75, 1.0, v75
	v_add_f32_e32 v76, 1.0, v76
	v_add_f32_e32 v77, 1.0, v77
	v_rcp_f32_e32 v70, v70
	v_rcp_f32_e32 v71, v71
	v_rcp_f32_e32 v74, v74
	v_rcp_f32_e32 v75, v75
	v_rcp_f32_e32 v76, v76
	v_rcp_f32_e32 v77, v77
	v_pk_mul_f32 v[70:71], v[94:95], v[70:71]
	v_pk_mul_f32 v[74:75], v[96:97], v[74:75]
	v_pk_mul_f32 v[70:71], v[78:79], v[70:71]
	v_pk_mul_f32 v[76:77], v[98:99], v[76:77]
	v_pk_mul_f32 v[74:75], v[80:81], v[74:75]
	v_pk_mul_f32 v[76:77], v[82:83], v[76:77]
	v_cvt_pk_bf16_f32 v68, v68, v69
	v_cvt_pk_bf16_f32 v69, v70, v71
	v_cvt_pk_bf16_f32 v70, v74, v75
	v_cvt_pk_bf16_f32 v71, v76, v77
	global_store_dwordx4 v[72:73], v[68:71], off offset:16
	s_nop 1
	v_mul_f32_e32 v70, 0xbfb8aa3b, v52
	v_mul_f32_e32 v71, 0xbfb8aa3b, v53
	v_exp_f32_e32 v70, v70
	v_exp_f32_e32 v71, v71
	v_or_b32_e32 v68, 64, v134
	v_mad_i64_i32 v[68:69], s[4:5], v68, s8, v[132:133]
	v_add_f32_e32 v70, 1.0, v70
	v_add_f32_e32 v71, 1.0, v71
	v_rcp_f32_e32 v70, v70
	v_rcp_f32_e32 v71, v71
	s_nop 0
	v_pk_mul_f32 v[52:53], v[52:53], v[70:71]
	s_nop 0
	v_pk_mul_f32 v[36:37], v[36:37], v[52:53]
	v_mul_f32_e32 v52, 0xbfb8aa3b, v54
	v_mul_f32_e32 v53, 0xbfb8aa3b, v55
	v_exp_f32_e32 v52, v52
	v_exp_f32_e32 v53, v53
	v_cvt_pk_bf16_f32 v36, v36, v37
	v_add_f32_e32 v52, 1.0, v52
	v_add_f32_e32 v53, 1.0, v53
	v_rcp_f32_e32 v52, v52
	v_rcp_f32_e32 v53, v53
	s_nop 0
; DI int bid_l() { int t = blockIdx.x; asm volatile("" : "+s"(t)); return t; }
; DI unsigned pack2(float a, float b) { f2_t v = {a, b}; return __builtin_bit_cast(unsigned, __builtin_convertvector(v, bf2_t)); }
; DI float siluf(float x) { return x * __builtin_amdgcn_rcpf(1.f + __expf(-x)); }
; template <int MF, int BK, class Epi>
; DI void gemm_phase_t(char* lds, const GemmDesc g, const Epi epi) {
;     ...
;   for (int t = bid_l(); t < ntiles; t += gridDim.x) {
;   template <int MF> DI void operator()(f32x16 (&acc)[MF][2], int mb, int nb, int l31, int h) const {
;     ...
;     for (int mi = 0; mi < MF; ++mi) {
;       const int row = mb + mi * 32 + l31;
; #pragma unroll
;       for (int gp = 0; gp < 2; ++gp) {
;         const int j0 = (nb >> 1) + 16 * h + 8 * gp;
;         float v[8];
; #pragma unroll
;         for (int i = 0; i < 8; ++i) v[i] = siluf(acc[mi][0][8 * gp + i]) * acc[mi][1][8 * gp + i];
;         *(u32x4*)(act + (size_t)row * FF + j0) = (u32x4){pack2(v[0], v[1]), pack2(v[2], v[3]), pack2(v[4], v[5]), pack2(v[6], v[7])};
;       }
	v_pk_mul_f32 v[52:53], v[54:55], v[52:53]
	s_nop 0
	v_pk_mul_f32 v[38:39], v[38:39], v[52:53]
	v_mul_f32_e32 v52, 0xbfb8aa3b, v56
	v_mul_f32_e32 v53, 0xbfb8aa3b, v57
	v_exp_f32_e32 v52, v52
	v_exp_f32_e32 v53, v53
	v_cvt_pk_bf16_f32 v37, v38, v39
	v_add_f32_e32 v52, 1.0, v52
	v_add_f32_e32 v53, 1.0, v53
	v_rcp_f32_e32 v52, v52
	v_rcp_f32_e32 v53, v53
	s_nop 0
	v_pk_mul_f32 v[52:53], v[56:57], v[52:53]
	s_nop 0
	v_pk_mul_f32 v[40:41], v[40:41], v[52:53]
	v_mul_f32_e32 v52, 0xbfb8aa3b, v58
	v_mul_f32_e32 v53, 0xbfb8aa3b, v59
	v_exp_f32_e32 v52, v52
	v_exp_f32_e32 v53, v53
	v_cvt_pk_bf16_f32 v38, v40, v41
	v_lshl_add_u64 v[40:41], v[68:69], 0, v[100:101]
	v_add_f32_e32 v52, 1.0, v52
	v_add_f32_e32 v53, 1.0, v53
	v_rcp_f32_e32 v52, v52
	v_rcp_f32_e32 v53, v53
	s_nop 0
	v_pk_mul_f32 v[52:53], v[58:59], v[52:53]
	s_nop 0
	v_pk_mul_f32 v[42:43], v[42:43], v[52:53]
	s_nop 0
	v_cvt_pk_bf16_f32 v39, v42, v43
	global_store_dwordx4 v[40:41], v[36:39], off
	v_mul_f32_e32 v42, 0xbfb8aa3b, v64
	v_mul_f32_e32 v43, 0xbfb8aa3b, v65
	v_mul_f32_e32 v36, 0xbfb8aa3b, v60
	v_mul_f32_e32 v37, 0xbfb8aa3b, v61
	v_exp_f32_e32 v36, v36
	v_exp_f32_e32 v37, v37
	v_mul_f32_e32 v38, 0xbfb8aa3b, v62
	v_mul_f32_e32 v39, 0xbfb8aa3b, v63
	v_add_f32_e32 v36, 1.0, v36
	v_add_f32_e32 v37, 1.0, v37
	v_rcp_f32_e32 v36, v36
	v_rcp_f32_e32 v37, v37
	v_exp_f32_e32 v38, v38
	v_exp_f32_e32 v39, v39
	v_exp_f32_e32 v42, v42
	v_pk_mul_f32 v[36:37], v[60:61], v[36:37]
	v_exp_f32_e32 v43, v43
	v_pk_mul_f32 v[36:37], v[44:45], v[36:37]
	v_mul_f32_e32 v44, 0xbfb8aa3b, v66
	v_mul_f32_e32 v45, 0xbfb8aa3b, v67
	v_exp_f32_e32 v44, v44
	v_exp_f32_e32 v45, v45
	v_add_f32_e32 v38, 1.0, v38
	v_add_f32_e32 v39, 1.0, v39
	v_add_f32_e32 v42, 1.0, v42
	v_add_f32_e32 v43, 1.0, v43
	v_add_f32_e32 v44, 1.0, v44
	v_add_f32_e32 v45, 1.0, v45
	v_rcp_f32_e32 v38, v38
	v_rcp_f32_e32 v39, v39
	v_rcp_f32_e32 v42, v42
	v_rcp_f32_e32 v43, v43
	v_rcp_f32_e32 v44, v44
	v_rcp_f32_e32 v45, v45
	v_pk_mul_f32 v[38:39], v[62:63], v[38:39]
	v_pk_mul_f32 v[42:43], v[64:65], v[42:43]
	v_pk_mul_f32 v[38:39], v[46:47], v[38:39]
	v_pk_mul_f32 v[44:45], v[66:67], v[44:45]
	v_pk_mul_f32 v[42:43], v[48:49], v[42:43]
	v_pk_mul_f32 v[44:45], v[50:51], v[44:45]
	v_cvt_pk_bf16_f32 v36, v36, v37
	v_cvt_pk_bf16_f32 v37, v38, v39
	v_cvt_pk_bf16_f32 v38, v42, v43
	v_cvt_pk_bf16_f32 v39, v44, v45
	global_store_dwordx4 v[40:41], v[36:39], off offset:16
	s_nop 1
	v_mul_f32_e32 v38, 0xbfb8aa3b, v20
	v_mul_f32_e32 v39, 0xbfb8aa3b, v21
	v_exp_f32_e32 v38, v38
	v_exp_f32_e32 v39, v39
	v_or_b32_e32 v36, 0x60, v134
	v_mad_i64_i32 v[36:37], s[4:5], v36, s8, v[132:133]
	v_add_f32_e32 v38, 1.0, v38
	v_add_f32_e32 v39, 1.0, v39
	v_rcp_f32_e32 v38, v38
	v_rcp_f32_e32 v39, v39
	v_readlane_b32 s4, v252, 40
	s_add_i32 s7, s7, s4
	s_cmp_ge_i32 s7, s6
	v_pk_mul_f32 v[20:21], v[20:21], v[38:39]
	v_readlane_b32 s5, v252, 41
	v_pk_mul_f32 v[4:5], v[4:5], v[20:21]
	v_mul_f32_e32 v20, 0xbfb8aa3b, v22
	v_mul_f32_e32 v21, 0xbfb8aa3b, v23
	v_exp_f32_e32 v20, v20
	v_exp_f32_e32 v21, v21
	v_cvt_pk_bf16_f32 v4, v4, v5
	v_add_f32_e32 v20, 1.0, v20
	v_add_f32_e32 v21, 1.0, v21
	v_rcp_f32_e32 v20, v20
	v_rcp_f32_e32 v21, v21
	s_nop 0
	v_pk_mul_f32 v[20:21], v[22:23], v[20:21]
	s_nop 0
	v_pk_mul_f32 v[6:7], v[6:7], v[20:21]
	v_mul_f32_e32 v20, 0xbfb8aa3b, v24
	v_mul_f32_e32 v21, 0xbfb8aa3b, v25
	v_exp_f32_e32 v20, v20
	v_exp_f32_e32 v21, v21
	v_cvt_pk_bf16_f32 v5, v6, v7
	v_add_f32_e32 v20, 1.0, v20
	v_add_f32_e32 v21, 1.0, v21
	v_rcp_f32_e32 v20, v20
	v_rcp_f32_e32 v21, v21
	s_nop 0
	v_pk_mul_f32 v[20:21], v[24:25], v[20:21]
	s_nop 0
	v_pk_mul_f32 v[8:9], v[8:9], v[20:21]
	v_mul_f32_e32 v20, 0xbfb8aa3b, v26
	v_mul_f32_e32 v21, 0xbfb8aa3b, v27
	v_exp_f32_e32 v20, v20
	v_exp_f32_e32 v21, v21
	v_cvt_pk_bf16_f32 v6, v8, v9
	v_lshl_add_u64 v[8:9], v[36:37], 0, v[100:101]
	v_add_f32_e32 v20, 1.0, v20
	v_add_f32_e32 v21, 1.0, v21
	v_rcp_f32_e32 v20, v20
	v_rcp_f32_e32 v21, v21
	s_nop 0
	v_pk_mul_f32 v[20:21], v[26:27], v[20:21]
	s_nop 0
	v_pk_mul_f32 v[10:11], v[10:11], v[20:21]
	s_nop 0
	v_cvt_pk_bf16_f32 v7, v10, v11
	global_store_dwordx4 v[8:9], v[4:7], off
	v_mul_f32_e32 v10, 0xbfb8aa3b, v32
	v_mul_f32_e32 v11, 0xbfb8aa3b, v33
	v_mul_f32_e32 v4, 0xbfb8aa3b, v28
	v_mul_f32_e32 v5, 0xbfb8aa3b, v29
	v_exp_f32_e32 v4, v4
	v_exp_f32_e32 v5, v5
	v_mul_f32_e32 v6, 0xbfb8aa3b, v30
	v_mul_f32_e32 v7, 0xbfb8aa3b, v31
	v_add_f32_e32 v4, 1.0, v4
	v_add_f32_e32 v5, 1.0, v5
	v_rcp_f32_e32 v4, v4
	v_rcp_f32_e32 v5, v5
	v_exp_f32_e32 v6, v6
	v_exp_f32_e32 v7, v7
	v_exp_f32_e32 v10, v10
	v_pk_mul_f32 v[4:5], v[28:29], v[4:5]
	v_exp_f32_e32 v11, v11
	v_pk_mul_f32 v[4:5], v[12:13], v[4:5]
	v_mul_f32_e32 v12, 0xbfb8aa3b, v34
	v_mul_f32_e32 v13, 0xbfb8aa3b, v35
	v_exp_f32_e32 v12, v12
	v_exp_f32_e32 v13, v13
	v_add_f32_e32 v6, 1.0, v6
	v_add_f32_e32 v7, 1.0, v7
	v_add_f32_e32 v10, 1.0, v10
	v_add_f32_e32 v11, 1.0, v11
	v_add_f32_e32 v12, 1.0, v12
	v_add_f32_e32 v13, 1.0, v13
	v_rcp_f32_e32 v6, v6
	v_rcp_f32_e32 v7, v7
	v_rcp_f32_e32 v10, v10
	v_rcp_f32_e32 v11, v11
	v_rcp_f32_e32 v12, v12
	v_rcp_f32_e32 v13, v13
	v_pk_mul_f32 v[6:7], v[30:31], v[6:7]
	v_pk_mul_f32 v[10:11], v[32:33], v[10:11]
	v_pk_mul_f32 v[6:7], v[14:15], v[6:7]
	v_pk_mul_f32 v[12:13], v[34:35], v[12:13]
	v_pk_mul_f32 v[10:11], v[16:17], v[10:11]
	v_pk_mul_f32 v[12:13], v[18:19], v[12:13]
	v_cvt_pk_bf16_f32 v4, v4, v5
	v_cvt_pk_bf16_f32 v5, v6, v7
	v_cvt_pk_bf16_f32 v6, v10, v11
	v_cvt_pk_bf16_f32 v7, v12, v13
	global_store_dwordx4 v[8:9], v[4:7], off offset:16
	s_cbranch_scc0 .LBB0_287

; #define MFMA32(a, b, c) __builtin_amdgcn_mfma_f32_32x32x16_bf16((a), (b), (c), 0, 0, 0)
; template <int MF, int BK, class Epi>
; DI void gemm_phase_t(char* lds, const GemmDesc g, const Epi epi) {
;     ...
;     for (int kt = 0; kt < nk; ++kt) {
;       __syncthreads();
;       const u16* sA = sbase + (kt & 1) * STG;
;       const u16* sB = sA + BM * LS;
;       if (kt + 1 < nk) {
;         u16* nA = sbase + ((kt + 1) & 1) * STG;
; #pragma unroll
;         for (int j = 0; j < APT; ++j) *(u32x4*)(nA + (lr + RSTEP * j) * LS + lc * 8) = ra[j];
; #pragma unroll
;         for (int j = 0; j < BPT; ++j) *(u32x4*)(nA + BM * LS + (lr + RSTEP * j) * LS + lc * 8) = rb[j];
;         if (kt + 2 < nk) {
; #pragma unroll
;           for (int j = 0; j < APT; ++j) ra[j] = *(const u32x4*)(Ap + (size_t)j * RSTEP * g.lda + (kt + 2) * BK);
; #pragma unroll
;           for (int j = 0; j < BPT; ++j) rb[j] = *(const u32x4*)(Bp + (size_t)j * RSTEP * g.ldb + (kt + 2) * BK);
;         }
;       }
;       bf16x8 af[NKK][MF], bfr[NKK][2];
; #pragma unroll
;       for (int kk = 0; kk < NKK; ++kk) {
; #pragma unroll
;         for (int ni = 0; ni < 2; ++ni) bfr[kk][ni] = *(const bf16x8*)(sB + (wn * 64 + ni * 32 + l31) * LS + kk * 16 + h * 8);
; #pragma unroll
;         for (int mi = 0; mi < MF; ++mi) af[kk][mi] = *(const bf16x8*)(sA + (wm * (MF * 32) + mi * 32 + l31) * LS + kk * 16 + h * 8);
;       }
;       __builtin_amdgcn_sched_barrier(0);
; #pragma unroll
;       for (int kk = 0; kk < NKK; ++kk)
; #pragma unroll
;         for (int mi = 0; mi < MF; ++mi)
; #pragma unroll
;           for (int ni = 0; ni < 2; ++ni) acc[mi][ni] = MFMA32(bfr[kk][ni], af[kk][mi], acc[mi][ni]);
.LBB0_954:
	v_lshl_add_u64 v[182:183], v[162:163], 0, s[0:1]
	v_add_co_u32_e32 v194, vcc, s5, v182
	v_lshl_add_u64 v[190:191], v[164:165], 0, s[0:1]
	s_nop 0
	v_addc_co_u32_e32 v195, vcc, 0, v183, vcc
	v_add_co_u32_e32 v198, vcc, s11, v182
	s_mov_b32 s4, 0xc4c000
	s_nop 0
	v_addc_co_u32_e32 v199, vcc, 0, v183, vcc
	v_add_co_u32_e32 v200, vcc, s12, v182
	s_waitcnt lgkmcnt(0)
	s_nop 0
	v_addc_co_u32_e32 v201, vcc, 0, v183, vcc
	v_add_co_u32_e32 v204, vcc, s13, v182
	s_waitcnt vmcnt(6)
	s_barrier
	s_nop 0
	v_addc_co_u32_e32 v205, vcc, 0, v183, vcc
	v_add_co_u32_e32 v206, vcc, s4, v190
	s_mov_b32 s4, 0xc6c000
	s_nop 0
	v_addc_co_u32_e32 v207, vcc, 0, v191, vcc
	v_add_co_u32_e32 v246, vcc, s4, v190
	s_add_i32 m0, s100, 0xffffff80
	s_nop 0
	global_load_lds_dwordx4 v[194:195], off offset:128
	s_add_i32 m0, s100, 0xf80
	s_nop 0
	global_load_lds_dwordx4 v[198:199], off offset:128
	s_add_i32 m0, s100, 0x1f80
	s_nop 0
	global_load_lds_dwordx4 v[200:201], off offset:128
	s_add_i32 m0, s100, 0x2f80
	s_nop 0
	global_load_lds_dwordx4 v[204:205], off offset:128
	v_addc_co_u32_e32 v247, vcc, 0, v191, vcc
	s_add_i32 m0, s100, 0x3f80
	s_nop 0
	global_load_lds_dwordx4 v[206:207], off offset:128
	s_add_i32 m0, s100, 0x4f80
	s_nop 0
	global_load_lds_dwordx4 v[246:247], off offset:128
	v_add_u32_e32 v174, s98, v172
	v_add_u32_e32 v175, s98, v173
	v_add_u32_e32 v176, s98, v171
	v_add_u32_e32 v177, s98, v170
	ds_read_b128 v[132:135], v176
	ds_read_b128 v[222:225], v177
	ds_read_b128 v[136:139], v176 offset:2048
	ds_read_b128 v[226:229], v177 offset:2048
	ds_read_b128 v[140:143], v174
	ds_read_b128 v[144:147], v175
	ds_read_b128 v[148:151], v174 offset:2048
	ds_read_b128 v[152:155], v175 offset:2048
	ds_read_b128 v[230:233], v174 offset:4096
	ds_read_b128 v[234:237], v175 offset:4096
	ds_read_b128 v[238:241], v174 offset:6144
	ds_read_b128 v[242:245], v175 offset:6144
	s_waitcnt lgkmcnt(7)
	v_mfma_f32_32x32x16_bf16 v[116:131], v[132:135], v[140:143], v[116:131]
	s_waitcnt lgkmcnt(0)
	s_waitcnt vmcnt(6)
	s_barrier
	v_mfma_f32_32x32x16_bf16 v[100:115], v[136:139], v[140:143], v[100:115]
	s_add_i32 m0, s98, 0xffffff40
	s_nop 0
	global_load_lds_dwordx4 v[194:195], off offset:192
	v_mfma_f32_32x32x16_bf16 v[84:99], v[132:135], v[148:151], v[84:99]
	s_add_i32 m0, s98, 0xf40
	s_nop 0
	global_load_lds_dwordx4 v[198:199], off offset:192
	v_mfma_f32_32x32x16_bf16 v[68:83], v[136:139], v[148:151], v[68:83]
	s_add_i32 m0, s98, 0x1f40
	s_nop 0
	global_load_lds_dwordx4 v[200:201], off offset:192
	v_mfma_f32_32x32x16_bf16 v[52:67], v[132:135], v[230:233], v[52:67]
	s_add_i32 m0, s98, 0x2f40
	s_nop 0
	global_load_lds_dwordx4 v[204:205], off offset:192
	v_mfma_f32_32x32x16_bf16 v[36:51], v[136:139], v[230:233], v[36:51]
	s_add_i32 m0, s98, 0x3f40
	s_nop 0
	global_load_lds_dwordx4 v[206:207], off offset:192
	v_mfma_f32_32x32x16_bf16 v[20:35], v[132:135], v[238:241], v[20:35]
	s_add_i32 m0, s98, 0x4f40
	s_nop 0
	global_load_lds_dwordx4 v[246:247], off offset:192
	v_mfma_f32_32x32x16_bf16 v[4:19], v[136:139], v[238:241], v[4:19]
	v_mfma_f32_32x32x16_bf16 v[116:131], v[222:225], v[144:147], v[116:131]
	v_mfma_f32_32x32x16_bf16 v[100:115], v[226:229], v[144:147], v[100:115]
	v_mfma_f32_32x32x16_bf16 v[84:99], v[222:225], v[152:155], v[84:99]
	v_mfma_f32_32x32x16_bf16 v[68:83], v[226:229], v[152:155], v[68:83]
	v_add_u32_e32 v132, s99, v172
	v_add_u32_e32 v133, s99, v173
	v_add_u32_e32 v134, s99, v171
	v_add_u32_e32 v135, s99, v170
	ds_read_b128 v[174:177], v134
	ds_read_b128 v[178:181], v135
	ds_read_b128 v[182:185], v134 offset:2048
	ds_read_b128 v[186:189], v135 offset:2048
	v_mfma_f32_32x32x16_bf16 v[52:67], v[222:225], v[234:237], v[52:67]
	v_mfma_f32_32x32x16_bf16 v[36:51], v[226:229], v[234:237], v[36:51]
	v_mfma_f32_32x32x16_bf16 v[20:35], v[222:225], v[242:245], v[20:35]
	ds_read_b128 v[190:193], v132
	ds_read_b128 v[218:221], v133
	ds_read_b128 v[222:225], v132 offset:2048
	ds_read_b128 v[230:233], v133 offset:2048
	ds_read_b128 v[234:237], v132 offset:4096
	ds_read_b128 v[238:241], v133 offset:4096
	ds_read_b128 v[246:249], v132 offset:6144
	ds_read_b128 v[204:207], v133 offset:6144
	v_mfma_f32_32x32x16_bf16 v[4:19], v[226:229], v[242:245], v[4:19]
	s_waitcnt lgkmcnt(7)
	v_mfma_f32_32x32x16_bf16 v[116:131], v[174:177], v[190:193], v[116:131]
	s_add_u32 s0, s0, 0x80
	s_addc_u32 s1, s1, 0
	s_cmpk_eq_i32 s0, 0x780
	v_mfma_f32_32x32x16_bf16 v[100:115], v[182:185], v[190:193], v[100:115]
	s_waitcnt lgkmcnt(5)
	v_mfma_f32_32x32x16_bf16 v[84:99], v[174:177], v[222:225], v[84:99]
	v_mfma_f32_32x32x16_bf16 v[68:83], v[182:185], v[222:225], v[68:83]
	s_waitcnt lgkmcnt(3)
	v_mfma_f32_32x32x16_bf16 v[52:67], v[174:177], v[234:237], v[52:67]
	v_mfma_f32_32x32x16_bf16 v[36:51], v[182:185], v[234:237], v[36:51]
	s_waitcnt lgkmcnt(1)
	v_mfma_f32_32x32x16_bf16 v[20:35], v[174:177], v[246:249], v[20:35]
	v_mfma_f32_32x32x16_bf16 v[4:19], v[182:185], v[246:249], v[4:19]
	v_mfma_f32_32x32x16_bf16 v[116:131], v[178:181], v[218:221], v[116:131]
	v_mfma_f32_32x32x16_bf16 v[100:115], v[186:189], v[218:221], v[100:115]
	v_mfma_f32_32x32x16_bf16 v[84:99], v[178:181], v[230:233], v[84:99]
	v_mfma_f32_32x32x16_bf16 v[68:83], v[186:189], v[230:233], v[68:83]
	v_mfma_f32_32x32x16_bf16 v[52:67], v[178:181], v[238:241], v[52:67]
	v_mfma_f32_32x32x16_bf16 v[36:51], v[186:189], v[238:241], v[36:51]
	s_waitcnt lgkmcnt(0)
	v_mfma_f32_32x32x16_bf16 v[20:35], v[178:181], v[204:207], v[20:35]
	v_mfma_f32_32x32x16_bf16 v[4:19], v[186:189], v[204:207], v[4:19]
	s_mov_b32 s101, s100
	s_mov_b32 s100, s99
	s_mov_b32 s99, s98
	s_mov_b32 s98, s101
	s_cbranch_scc0 .LBB0_954
	s_waitcnt vmcnt(6)
	s_barrier
; #define MFMA32(a, b, c) __builtin_amdgcn_mfma_f32_32x32x16_bf16((a), (b), (c), 0, 0, 0)
; DI unsigned pack2(float a, float b) { f2_t v = {a, b}; return __builtin_bit_cast(unsigned, __builtin_convertvector(v, bf2_t)); }
; template <int MF, int BK, class Epi>
; DI void gemm_phase_t(char* lds, const GemmDesc g, const Epi epi) {
;     ...
;       for (int kk = 0; kk < NKK; ++kk) {
; #pragma unroll
;         for (int ni = 0; ni < 2; ++ni) bfr[kk][ni] = *(const bf16x8*)(sB + (wn * 64 + ni * 32 + l31) * LS + kk * 16 + h * 8);
; #pragma unroll
;         for (int mi = 0; mi < MF; ++mi) af[kk][mi] = *(const bf16x8*)(sA + (wm * (MF * 32) + mi * 32 + l31) * LS + kk * 16 + h * 8);
;       }
;       __builtin_amdgcn_sched_barrier(0);
; #pragma unroll
;       for (int kk = 0; kk < NKK; ++kk)
; #pragma unroll
;         for (int mi = 0; mi < MF; ++mi)
; #pragma unroll
;           for (int ni = 0; ni < 2; ++ni) acc[mi][ni] = MFMA32(bfr[kk][ni], af[kk][mi], acc[mi][ni]);
;   template <int MF> DI void operator()(f32x16 (&acc)[MF][2], int mb, int nb, int l31, int h) const {
;     ...
;       for (int g4 = 0; g4 < 4; ++g4) {
;         const int col0 = nb + 16 * g4 + 8 * h;
;         u16* dst = (col0 < 2560) ? zhg + (size_t)row * 2560 + col0 : zhy + (size_t)row * 1536 + (col0 - 2560);
;         *(u32x4*)dst = (u32x4){pack2(acc[mi][0][4 * g4], acc[mi][0][4 * g4 + 1]), pack2(acc[mi][0][4 * g4 + 2], acc[mi][0][4 * g4 + 3]),
;                                pack2(acc[mi][1][4 * g4], acc[mi][1][4 * g4 + 1]), pack2(acc[mi][1][4 * g4 + 2], acc[mi][1][4 * g4 + 3])};
	v_add_u32_e32 v222, s98, v172
	v_add_u32_e32 v223, s98, v173
	v_add_u32_e32 v224, s98, v171
	v_add_u32_e32 v225, s98, v170
	ds_read_b128 v[132:135], v224
	ds_read_b128 v[136:139], v225
	ds_read_b128 v[140:143], v224 offset:2048
	ds_read_b128 v[144:147], v225 offset:2048
	ds_read_b128 v[148:151], v222
	ds_read_b128 v[152:155], v223
	ds_read_b128 v[162:165], v222 offset:2048
	ds_read_b128 v[174:177], v223 offset:2048
	ds_read_b128 v[178:181], v222 offset:4096
	ds_read_b128 v[182:185], v223 offset:4096
	ds_read_b128 v[186:189], v222 offset:6144
	ds_read_b128 v[190:193], v223 offset:6144
	s_waitcnt lgkmcnt(7)
	v_mfma_f32_32x32x16_bf16 v[116:131], v[132:135], v[148:151], v[116:131]
	s_waitcnt lgkmcnt(0)
	s_waitcnt vmcnt(0)
	s_barrier
	v_mfma_f32_32x32x16_bf16 v[100:115], v[140:143], v[148:151], v[100:115]
	v_mfma_f32_32x32x16_bf16 v[84:99], v[132:135], v[162:165], v[84:99]
	v_mfma_f32_32x32x16_bf16 v[68:83], v[140:143], v[162:165], v[68:83]
	v_mfma_f32_32x32x16_bf16 v[52:67], v[132:135], v[178:181], v[52:67]
	v_mfma_f32_32x32x16_bf16 v[36:51], v[140:143], v[178:181], v[36:51]
	v_mfma_f32_32x32x16_bf16 v[20:35], v[132:135], v[186:189], v[20:35]
	v_mfma_f32_32x32x16_bf16 v[4:19], v[140:143], v[186:189], v[4:19]
	v_mfma_f32_32x32x16_bf16 v[116:131], v[136:139], v[152:155], v[116:131]
	v_mfma_f32_32x32x16_bf16 v[100:115], v[144:147], v[152:155], v[100:115]
	v_mfma_f32_32x32x16_bf16 v[84:99], v[136:139], v[174:177], v[84:99]
	v_mfma_f32_32x32x16_bf16 v[68:83], v[144:147], v[174:177], v[68:83]
	v_mfma_f32_32x32x16_bf16 v[52:67], v[136:139], v[182:185], v[52:67]
	v_mfma_f32_32x32x16_bf16 v[36:51], v[144:147], v[182:185], v[36:51]
	v_mfma_f32_32x32x16_bf16 v[20:35], v[136:139], v[190:193], v[20:35]
	v_mfma_f32_32x32x16_bf16 v[4:19], v[144:147], v[190:193], v[4:19]
	v_add_u32_e32 v226, s99, v172
	v_add_u32_e32 v227, s99, v173
	v_add_u32_e32 v228, s99, v171
	v_add_u32_e32 v229, s99, v170
	s_mov_b32 s101, s100
	s_mov_b32 s100, s99
	s_mov_b32 s99, s98
	s_mov_b32 s98, s101
	ds_read_b128 v[132:135], v226 offset:6144
	ds_read_b128 v[136:139], v227 offset:6144
	ds_read_b128 v[140:143], v227 offset:4096
	ds_read_b128 v[144:147], v227 offset:2048
	ds_read_b128 v[148:151], v226
	ds_read_b128 v[152:155], v227
	ds_read_b128 v[162:165], v229 offset:2048
	ds_read_b128 v[174:177], v228
	ds_read_b128 v[178:181], v229
	ds_read_b128 v[182:185], v226 offset:4096
	ds_read_b128 v[186:189], v226 offset:2048
	ds_read_b128 v[190:193], v228 offset:2048
	s_waitcnt lgkmcnt(4)
	v_mfma_f32_32x32x16_bf16 v[116:131], v[174:177], v[148:151], v[116:131]
	s_movk_i32 s0, 0xa00
	s_movk_i32 s11, 0x1400
	s_movk_i32 s14, 0xc00
	s_movk_i32 s16, 0xec00
	s_mov_b32 s17, -1
	s_movk_i32 s18, 0xec20
	s_mov_b32 s19, -1
	s_waitcnt lgkmcnt(0)
	v_mfma_f32_32x32x16_bf16 v[100:115], v[190:193], v[148:151], v[100:115]
	v_add_u32_e32 v148, s2, v168
	s_movk_i32 s20, 0xec40
	s_movk_i32 s2, 0x9e0
	s_mov_b32 s21, -1
	s_movk_i32 s24, 0xec60
	s_movk_i32 s4, 0x9d0
	s_mov_b64 s[22:23], 0x60
	v_mfma_f32_32x32x16_bf16 v[52:67], v[174:177], v[182:185], v[52:67]
	s_mov_b32 s25, -1
	v_mfma_f32_32x32x16_bf16 v[36:51], v[190:193], v[182:185], v[36:51]
	v_mfma_f32_32x32x16_bf16 v[20:35], v[174:177], v[132:135], v[20:35]
	v_mfma_f32_32x32x16_bf16 v[4:19], v[190:193], v[132:135], v[4:19]
	v_mov_b64_e32 v[134:135], s[6:7]
	v_mov_b64_e32 v[132:133], s[8:9]
	v_mfma_f32_32x32x16_bf16 v[84:99], v[174:177], v[186:189], v[84:99]
	v_mfma_f32_32x32x16_bf16 v[68:83], v[190:193], v[186:189], v[68:83]
	v_mfma_f32_32x32x16_bf16 v[116:131], v[178:181], v[152:155], v[116:131]
	v_mfma_f32_32x32x16_bf16 v[100:115], v[162:165], v[152:155], v[100:115]
	s_nop 10
	v_cvt_pk_bf16_f32 v116, v116, v117
	v_cvt_pk_bf16_f32 v117, v118, v119
	v_mfma_f32_32x32x16_bf16 v[52:67], v[178:181], v[140:143], v[52:67]
	v_cvt_pk_bf16_f32 v118, v100, v101
	v_cvt_pk_bf16_f32 v119, v102, v103
	v_mfma_f32_32x32x16_bf16 v[36:51], v[162:165], v[140:143], v[36:51]
	v_or_b32_e32 v140, s3, v169
	v_ashrrev_i32_e32 v141, 31, v140
	v_cmp_gt_i32_e32 vcc, s0, v140
	v_mad_i64_i32 v[142:143], s[0:1], v148, s14, v[132:133]
	v_cmp_gt_i32_e64 s[2:3], s2, v140
	v_cmp_gt_i32_e64 s[4:5], s4, v140
	v_mfma_f32_32x32x16_bf16 v[20:35], v[178:181], v[136:139], v[20:35]
	s_nop 1
	v_cvt_pk_bf16_f32 v52, v52, v53
	v_cvt_pk_bf16_f32 v53, v54, v55
	s_nop 0
	v_cvt_pk_bf16_f32 v54, v36, v37
	v_cvt_pk_bf16_f32 v55, v38, v39
	v_mfma_f32_32x32x16_bf16 v[4:19], v[162:165], v[136:139], v[4:19]
	v_mad_i64_i32 v[138:139], s[0:1], v148, s11, v[134:135]
	v_lshlrev_b64 v[136:137], 1, v[140:141]
	v_mov_b32_e32 v141, v3
	s_movk_i32 s0, 0x9f0
	v_cmp_gt_i32_e64 s[0:1], s0, v140
	v_cvt_pk_bf16_f32 v20, v20, v21
	v_mfma_f32_32x32x16_bf16 v[84:99], v[178:181], v[144:147], v[84:99]
	v_cvt_pk_bf16_f32 v21, v22, v23
	s_nop 3
	v_cvt_pk_bf16_f32 v22, v4, v5
	v_cvt_pk_bf16_f32 v23, v6, v7
	v_mfma_f32_32x32x16_bf16 v[68:83], v[162:165], v[144:147], v[68:83]
	v_lshl_add_u64 v[144:145], v[138:139], 0, v[136:137]
	v_lshlrev_b64 v[138:139], 1, v[140:141]
	v_lshl_add_u64 v[142:143], v[142:143], 0, v[138:139]
	v_lshl_add_u64 v[146:147], v[142:143], 0, s[16:17]
	v_cndmask_b32_e32 v147, v147, v145, vcc
	v_cndmask_b32_e32 v146, v146, v144, vcc
	v_lshl_add_u64 v[100:101], v[144:145], 0, 32
	v_lshl_add_u64 v[102:103], v[142:143], 0, s[18:19]
	global_store_dwordx4 v[146:147], v[116:119], off
	v_cvt_pk_bf16_f32 v84, v84, v85
	v_cvt_pk_bf16_f32 v85, v86, v87
	v_cndmask_b32_e64 v117, v103, v101, s[0:1]
	v_cndmask_b32_e64 v116, v102, v100, s[0:1]
	v_cvt_pk_bf16_f32 v100, v120, v121
	v_cvt_pk_bf16_f32 v101, v122, v123
	v_cvt_pk_bf16_f32 v102, v104, v105
; DI int bid_l() { int t = blockIdx.x; asm volatile("" : "+s"(t)); return t; }
; DI unsigned pack2(float a, float b) { f2_t v = {a, b}; return __builtin_bit_cast(unsigned, __builtin_convertvector(v, bf2_t)); }
; template <int MF, int BK, class Epi>
; DI void gemm_phase_t(char* lds, const GemmDesc g, const Epi epi) {
;     ...
;   for (int t = bid_l(); t < ntiles; t += gridDim.x) {
;   template <int MF> DI void operator()(f32x16 (&acc)[MF][2], int mb, int nb, int l31, int h) const {
;     ...
;     for (int mi = 0; mi < MF; ++mi) {
;       const int row = mb + mi * 32 + l31;
; #pragma unroll
;       for (int g4 = 0; g4 < 4; ++g4) {
;         const int col0 = nb + 16 * g4 + 8 * h;
;         u16* dst = (col0 < 2560) ? zhg + (size_t)row * 2560 + col0 : zhy + (size_t)row * 1536 + (col0 - 2560);
;         *(u32x4*)dst = (u32x4){pack2(acc[mi][0][4 * g4], acc[mi][0][4 * g4 + 1]), pack2(acc[mi][0][4 * g4 + 2], acc[mi][0][4 * g4 + 3]),
;                                pack2(acc[mi][1][4 * g4], acc[mi][1][4 * g4 + 1]), pack2(acc[mi][1][4 * g4 + 2], acc[mi][1][4 * g4 + 3])};
	v_cvt_pk_bf16_f32 v103, v106, v107
	global_store_dwordx4 v[116:117], v[100:103], off
	v_cvt_pk_bf16_f32 v86, v68, v69
	v_cvt_pk_bf16_f32 v87, v70, v71
	v_lshl_add_u64 v[100:101], v[144:145], 0, 64
	v_lshl_add_u64 v[102:103], v[142:143], 0, s[20:21]
	v_cndmask_b32_e64 v105, v103, v101, s[2:3]
	v_cndmask_b32_e64 v104, v102, v100, s[2:3]
	v_cvt_pk_bf16_f32 v100, v124, v125
	v_cvt_pk_bf16_f32 v101, v126, v127
	v_cvt_pk_bf16_f32 v102, v108, v109
	v_cvt_pk_bf16_f32 v103, v110, v111
	global_store_dwordx4 v[104:105], v[100:103], off
	s_nop 1
	v_lshl_add_u64 v[100:101], v[144:145], 0, s[22:23]
	v_lshl_add_u64 v[102:103], v[142:143], 0, s[24:25]
	v_cndmask_b32_e64 v105, v103, v101, s[4:5]
	v_cndmask_b32_e64 v104, v102, v100, s[4:5]
	v_cvt_pk_bf16_f32 v100, v128, v129
	v_cvt_pk_bf16_f32 v101, v130, v131
	v_cvt_pk_bf16_f32 v102, v112, v113
	v_cvt_pk_bf16_f32 v103, v114, v115
	global_store_dwordx4 v[104:105], v[100:103], off
	s_nop 1
	v_or_b32_e32 v102, 32, v148
	v_mad_i64_i32 v[100:101], s[12:13], v102, s14, v[132:133]
	v_mad_i64_i32 v[102:103], s[12:13], v102, s11, v[134:135]
	v_lshl_add_u64 v[100:101], v[100:101], 0, v[138:139]
	v_lshl_add_u64 v[102:103], v[102:103], 0, v[136:137]
	v_lshl_add_u64 v[104:105], v[100:101], 0, s[16:17]
	v_cndmask_b32_e32 v105, v105, v103, vcc
	v_cndmask_b32_e32 v104, v104, v102, vcc
	v_lshl_add_u64 v[68:69], v[102:103], 0, 32
	v_lshl_add_u64 v[70:71], v[100:101], 0, s[18:19]
	global_store_dwordx4 v[104:105], v[84:87], off
	s_nop 1
	v_cndmask_b32_e64 v85, v71, v69, s[0:1]
	v_cndmask_b32_e64 v84, v70, v68, s[0:1]
	v_cvt_pk_bf16_f32 v68, v88, v89
	v_cvt_pk_bf16_f32 v69, v90, v91
	v_cvt_pk_bf16_f32 v70, v72, v73
	v_cvt_pk_bf16_f32 v71, v74, v75
	global_store_dwordx4 v[84:85], v[68:71], off
	s_nop 1
	v_lshl_add_u64 v[68:69], v[102:103], 0, 64
	v_lshl_add_u64 v[70:71], v[100:101], 0, s[20:21]
	v_cndmask_b32_e64 v73, v71, v69, s[2:3]
	v_cndmask_b32_e64 v72, v70, v68, s[2:3]
	v_cvt_pk_bf16_f32 v68, v92, v93
	v_cvt_pk_bf16_f32 v69, v94, v95
	v_cvt_pk_bf16_f32 v70, v76, v77
	v_cvt_pk_bf16_f32 v71, v78, v79
	global_store_dwordx4 v[72:73], v[68:71], off
	s_nop 1
	v_lshl_add_u64 v[68:69], v[102:103], 0, s[22:23]
	v_lshl_add_u64 v[70:71], v[100:101], 0, s[24:25]
	v_cndmask_b32_e64 v73, v71, v69, s[4:5]
	v_cndmask_b32_e64 v72, v70, v68, s[4:5]
	v_cvt_pk_bf16_f32 v68, v96, v97
	v_cvt_pk_bf16_f32 v69, v98, v99
	v_cvt_pk_bf16_f32 v70, v80, v81
	v_cvt_pk_bf16_f32 v71, v82, v83
	global_store_dwordx4 v[72:73], v[68:71], off
	s_nop 1
	v_or_b32_e32 v70, 64, v148
	v_mad_i64_i32 v[68:69], s[12:13], v70, s14, v[132:133]
	v_mad_i64_i32 v[70:71], s[12:13], v70, s11, v[134:135]
	v_lshl_add_u64 v[68:69], v[68:69], 0, v[138:139]
	v_lshl_add_u64 v[70:71], v[70:71], 0, v[136:137]
	v_lshl_add_u64 v[72:73], v[68:69], 0, s[16:17]
	v_cndmask_b32_e32 v73, v73, v71, vcc
	v_cndmask_b32_e32 v72, v72, v70, vcc
	v_lshl_add_u64 v[36:37], v[70:71], 0, 32
	v_lshl_add_u64 v[38:39], v[68:69], 0, s[18:19]
	global_store_dwordx4 v[72:73], v[52:55], off
	s_nop 1
	v_cndmask_b32_e64 v53, v39, v37, s[0:1]
	v_cndmask_b32_e64 v52, v38, v36, s[0:1]
	v_cvt_pk_bf16_f32 v36, v56, v57
	v_cvt_pk_bf16_f32 v37, v58, v59
	v_cvt_pk_bf16_f32 v38, v40, v41
	v_cvt_pk_bf16_f32 v39, v42, v43
	global_store_dwordx4 v[52:53], v[36:39], off
	s_nop 1
	v_lshl_add_u64 v[36:37], v[70:71], 0, 64
	v_lshl_add_u64 v[38:39], v[68:69], 0, s[20:21]
	v_cndmask_b32_e64 v41, v39, v37, s[2:3]
	v_cndmask_b32_e64 v40, v38, v36, s[2:3]
	v_cvt_pk_bf16_f32 v36, v60, v61
	v_cvt_pk_bf16_f32 v37, v62, v63
	v_cvt_pk_bf16_f32 v38, v44, v45
	v_cvt_pk_bf16_f32 v39, v46, v47
	global_store_dwordx4 v[40:41], v[36:39], off
	s_nop 1
	v_lshl_add_u64 v[36:37], v[70:71], 0, s[22:23]
	v_lshl_add_u64 v[38:39], v[68:69], 0, s[24:25]
	v_cndmask_b32_e64 v41, v39, v37, s[4:5]
	v_cndmask_b32_e64 v40, v38, v36, s[4:5]
	v_cvt_pk_bf16_f32 v36, v64, v65
	v_cvt_pk_bf16_f32 v37, v66, v67
	v_cvt_pk_bf16_f32 v38, v48, v49
	v_cvt_pk_bf16_f32 v39, v50, v51
	global_store_dwordx4 v[40:41], v[36:39], off
	s_nop 1
	v_or_b32_e32 v38, 0x60, v148
	v_mad_i64_i32 v[36:37], s[12:13], v38, s14, v[132:133]
	v_mad_i64_i32 v[38:39], s[12:13], v38, s11, v[134:135]
	v_lshl_add_u64 v[36:37], v[36:37], 0, v[138:139]
	v_lshl_add_u64 v[38:39], v[38:39], 0, v[136:137]
	v_lshl_add_u64 v[40:41], v[36:37], 0, s[16:17]
	v_cndmask_b32_e32 v41, v41, v39, vcc
	v_cndmask_b32_e32 v40, v40, v38, vcc
	v_lshl_add_u64 v[4:5], v[38:39], 0, 32
	v_lshl_add_u64 v[6:7], v[36:37], 0, s[18:19]
	global_store_dwordx4 v[40:41], v[20:23], off
	s_nop 1
	v_cndmask_b32_e64 v21, v7, v5, s[0:1]
	v_cndmask_b32_e64 v20, v6, v4, s[0:1]
	v_cvt_pk_bf16_f32 v4, v24, v25
	v_cvt_pk_bf16_f32 v5, v26, v27
	v_cvt_pk_bf16_f32 v6, v8, v9
	v_cvt_pk_bf16_f32 v7, v10, v11
	global_store_dwordx4 v[20:21], v[4:7], off
	v_readlane_b32 s0, v252, 40
	s_add_i32 s10, s10, s0
	v_lshl_add_u64 v[4:5], v[38:39], 0, 64
	v_lshl_add_u64 v[6:7], v[36:37], 0, s[20:21]
	v_cndmask_b32_e64 v9, v7, v5, s[2:3]
	v_cndmask_b32_e64 v8, v6, v4, s[2:3]
	v_cvt_pk_bf16_f32 v4, v28, v29
	v_cvt_pk_bf16_f32 v5, v30, v31
	v_cvt_pk_bf16_f32 v6, v12, v13
	v_cvt_pk_bf16_f32 v7, v14, v15
	global_store_dwordx4 v[8:9], v[4:7], off
	s_cmpk_gt_i32 s10, 0x10ff
	v_readlane_b32 s1, v252, 41
	v_lshl_add_u64 v[4:5], v[38:39], 0, s[22:23]
	v_lshl_add_u64 v[6:7], v[36:37], 0, s[24:25]
	v_cndmask_b32_e64 v9, v7, v5, s[4:5]
	v_cndmask_b32_e64 v8, v6, v4, s[4:5]
	v_cvt_pk_bf16_f32 v4, v32, v33
	v_cvt_pk_bf16_f32 v5, v34, v35
	v_cvt_pk_bf16_f32 v6, v16, v17
	v_cvt_pk_bf16_f32 v7, v18, v19
	global_store_dwordx4 v[8:9], v[4:7], off
	s_cbranch_scc0 .LBB0_953
